# speedup vs baseline: 1.0077x; 1.0077x over previous
; __device__ __forceinline__ void rmsnorm_rows(const float* x, const float* g, u16* H, int item, const int wv) {
;   const int tid = opaque_tid(wv);
;   const int wid = wv, lane = tid & 63;
;   const int row = item * 8 + wid;
;   const float4* xr = (const float4*)(x + (long)row * D);
;   float4 v[16]; float ss = 0.f;
;   #pragma unroll
;   for (int i = 0; i < 16; ++i) { v[i] = xr[i * 64 + lane]; ss += v[i].x * v[i].x + v[i].y * v[i].y + v[i].z * v[i].z + v[i].w * v[i].w; }
; __global__ void __launch_bounds__(512) fwd_megakernel(Params p) {
;     ...
;   for (int it = blockIdx.x; it < 2048; it += gridDim.x) rmsnorm_rows(p.out, p.g1, (u16*)(p.ws + OFF_H), it, wv);
.LBB0_515:
	s_or_b64 exec, exec, s[0:1]
	s_cmpk_gt_i32 s83, 0x7ff
	s_barrier
	s_cbranch_scc1 .LBB0_518
	s_lshl_b32 s0, s83, 3
	v_readlane_b32 s1, v255, 10
	s_add_i32 s4, s1, s0
	s_lshl_b32 s2, s91, 3
	v_mov_b32_e32 v64, 0x358637bd
	s_mov_b32 s3, 0xf800000
	v_mov_b32_e32 v65, 0x260
	s_mov_b32 s8, s83
	v_mbcnt_lo_u32_b32 v224, -1, 0
	v_mbcnt_hi_u32_b32 v224, -1, v224
	s_nop 0
	v_and_b32_e32 v224, 63, v224
	v_lshlrev_b32_e32 v224, 4, v224
	v_add_u32_e32 v225, 0x1000, v224
	v_add_u32_e32 v226, 0x2000, v224
	v_add_u32_e32 v227, 0x3000, v224
	global_load_dwordx4 v[160:163], v224, s[84:85]
	global_load_dwordx4 v[164:167], v224, s[84:85] offset:1024
	global_load_dwordx4 v[168:171], v224, s[84:85] offset:2048
	global_load_dwordx4 v[172:175], v224, s[84:85] offset:3072
	global_load_dwordx4 v[176:179], v225, s[84:85]
	global_load_dwordx4 v[180:183], v225, s[84:85] offset:1024
	global_load_dwordx4 v[184:187], v225, s[84:85] offset:2048
	global_load_dwordx4 v[188:191], v225, s[84:85] offset:3072
	global_load_dwordx4 v[192:195], v226, s[84:85]
	global_load_dwordx4 v[196:199], v226, s[84:85] offset:1024
	global_load_dwordx4 v[200:203], v226, s[84:85] offset:2048
	global_load_dwordx4 v[204:207], v226, s[84:85] offset:3072
	global_load_dwordx4 v[208:211], v227, s[84:85]
	global_load_dwordx4 v[212:215], v227, s[84:85] offset:1024
	global_load_dwordx4 v[216:219], v227, s[84:85] offset:2048
	global_load_dwordx4 v[220:223], v227, s[84:85] offset:3072
.LBB0_517:
	s_ashr_i32 s5, s4, 31
	v_mbcnt_lo_u32_b32 v0, -1, 0
	v_mbcnt_hi_u32_b32 v0, -1, v0
	s_lshl_b64 s[0:1], s[4:5], 14
	v_and_b32_e32 v69, 63, v0
	s_add_u32 s0, s70, s0
	v_or_b32_e32 v68, 0x380, v69
	s_addc_u32 s1, s71, s1
	v_lshlrev_b32_e32 v138, 4, v68
	v_or_b32_e32 v66, 0x3c0, v69
	v_lshlrev_b32_e32 v67, 4, v66
	global_load_dwordx4 v[4:7], v138, s[0:1]
	global_load_dwordx4 v[0:3], v67, s[0:1]
	v_lshlrev_b32_e32 v136, 4, v69
	global_load_dwordx4 v[60:63], v136, s[0:1]
	global_load_dwordx4 v[56:59], v136, s[0:1] offset:1024
	global_load_dwordx4 v[52:55], v136, s[0:1] offset:2048
	global_load_dwordx4 v[48:51], v136, s[0:1] offset:3072
	v_or_b32_e32 v137, 0x100, v69
	v_lshlrev_b32_e32 v139, 4, v137
	global_load_dwordx4 v[44:47], v139, s[0:1]
	v_or_b32_e32 v140, 0x140, v69
	v_lshlrev_b32_e32 v141, 4, v140
	global_load_dwordx4 v[40:43], v141, s[0:1]
	v_or_b32_e32 v142, 0x180, v69
	v_lshlrev_b32_e32 v143, 4, v142
	global_load_dwordx4 v[36:39], v143, s[0:1]
	v_or_b32_e32 v144, 0x1c0, v69
	v_lshlrev_b32_e32 v145, 4, v144
	global_load_dwordx4 v[32:35], v145, s[0:1]
	v_or_b32_e32 v146, 0x200, v69
	v_lshlrev_b32_e32 v147, 4, v146
	global_load_dwordx4 v[28:31], v147, s[0:1]
	v_or_b32_e32 v148, 0x240, v69
	v_lshlrev_b32_e32 v149, 4, v148
	global_load_dwordx4 v[24:27], v149, s[0:1]
	v_or_b32_e32 v150, 0x280, v69
	v_lshlrev_b32_e32 v151, 4, v150
	global_load_dwordx4 v[20:23], v151, s[0:1]
	v_or_b32_e32 v152, 0x2c0, v69
	v_lshlrev_b32_e32 v153, 4, v152
	global_load_dwordx4 v[16:19], v153, s[0:1]
	v_or_b32_e32 v154, 0x300, v69
	v_lshlrev_b32_e32 v155, 4, v154
	v_or_b32_e32 v156, 0x340, v69
	global_load_dwordx4 v[12:15], v155, s[0:1]
	v_lshlrev_b32_e32 v157, 4, v156
	global_load_dwordx4 v[8:11], v157, s[0:1]
	v_lshlrev_b32_e32 v158, 2, v69
	v_xor_b32_e32 v159, 0x80, v158
	v_lshlrev_b32_e32 v69, 3, v69
	s_waitcnt vmcnt(15)
	v_mov_b32_e32 v76, v5
	s_waitcnt vmcnt(14)
	v_mov_b32_e32 v77, v1
	v_mov_b32_e32 v74, v4
	v_mov_b32_e32 v75, v0
	v_pk_mul_f32 v[76:77], v[76:77], v[76:77]
	v_mov_b32_e32 v78, v6
	v_mov_b32_e32 v79, v2
	s_waitcnt vmcnt(13)
	v_pk_mul_f32 v[84:85], v[60:61], v[60:61]
	s_waitcnt vmcnt(12)
	v_pk_mul_f32 v[88:89], v[56:57], v[56:57]
	v_pk_fma_f32 v[74:75], v[74:75], v[74:75], v[76:77]
	v_pk_mul_f32 v[82:83], v[62:63], v[62:63]
	v_pk_mul_f32 v[86:87], v[58:59], v[58:59]
	v_pk_fma_f32 v[74:75], v[78:79], v[78:79], v[74:75]
	v_add_f32_e32 v78, v88, v89
	v_add_f32_e32 v79, v84, v85
	v_add_f32_e32 v78, v78, v86
	v_add_f32_e32 v79, v79, v82
	s_waitcnt vmcnt(11)
	v_pk_mul_f32 v[92:93], v[52:53], v[52:53]
	v_add_f32_e32 v78, v78, v87
	v_add_f32_e32 v79, v79, v83
	v_pk_mul_f32 v[90:91], v[54:55], v[54:55]
	v_add_f32_e32 v78, v79, v78
	v_add_f32_e32 v79, v92, v93
	v_add_f32_e32 v79, v79, v90
	s_waitcnt vmcnt(10)
	v_pk_mul_f32 v[96:97], v[48:49], v[48:49]
	v_add_f32_e32 v79, v79, v91
	v_pk_mul_f32 v[94:95], v[50:51], v[50:51]
	v_add_f32_e32 v78, v78, v79
	v_add_f32_e32 v79, v96, v97
	v_add_f32_e32 v79, v79, v94
	s_waitcnt vmcnt(9)
	v_pk_mul_f32 v[100:101], v[44:45], v[44:45]
	v_add_f32_e32 v79, v79, v95
	v_pk_mul_f32 v[98:99], v[46:47], v[46:47]
	v_add_f32_e32 v78, v78, v79
	v_add_f32_e32 v79, v100, v101
	v_add_f32_e32 v79, v79, v98
	s_waitcnt vmcnt(8)
	v_pk_mul_f32 v[104:105], v[40:41], v[40:41]
	v_add_f32_e32 v79, v79, v99
	v_pk_mul_f32 v[102:103], v[42:43], v[42:43]
	v_add_f32_e32 v78, v78, v79
	v_add_f32_e32 v79, v104, v105
	v_add_f32_e32 v79, v79, v102
	s_waitcnt vmcnt(7)
	v_pk_mul_f32 v[108:109], v[36:37], v[36:37]
	v_add_f32_e32 v79, v79, v103
	v_pk_mul_f32 v[106:107], v[38:39], v[38:39]
	v_add_f32_e32 v78, v78, v79
	v_add_f32_e32 v79, v108, v109
	v_add_f32_e32 v79, v79, v106
	s_waitcnt vmcnt(6)
	v_pk_mul_f32 v[112:113], v[32:33], v[32:33]
	v_add_f32_e32 v79, v79, v107
	v_pk_mul_f32 v[110:111], v[34:35], v[34:35]
	v_add_f32_e32 v78, v78, v79
	v_add_f32_e32 v79, v112, v113
	v_add_f32_e32 v79, v79, v110
	s_waitcnt vmcnt(5)
	v_pk_mul_f32 v[116:117], v[28:29], v[28:29]
	v_add_f32_e32 v79, v79, v111
	v_pk_mul_f32 v[114:115], v[30:31], v[30:31]
	v_add_f32_e32 v78, v78, v79
	v_add_f32_e32 v79, v116, v117
	v_add_f32_e32 v79, v79, v114
	s_waitcnt vmcnt(4)
; __device__ __forceinline__ void rmsnorm_rows(const float* x, const float* g, u16* H, int item, const int wv) {
;     ...
;   for (int i = 0; i < 16; ++i) { v[i] = xr[i * 64 + lane]; ss += v[i].x * v[i].x + v[i].y * v[i].y + v[i].z * v[i].z + v[i].w * v[i].w; }
;   #pragma unroll
;   for (int d = 32; d >= 1; d >>= 1) ss += sx(ss, d, lane);
	v_pk_mul_f32 v[120:121], v[24:25], v[24:25]
	v_add_f32_e32 v79, v79, v115
	v_pk_mul_f32 v[118:119], v[26:27], v[26:27]
	v_add_f32_e32 v78, v78, v79
	v_add_f32_e32 v79, v120, v121
	v_add_f32_e32 v79, v79, v118
	s_waitcnt vmcnt(3)
	v_pk_mul_f32 v[124:125], v[20:21], v[20:21]
	v_add_f32_e32 v79, v79, v119
	v_pk_mul_f32 v[122:123], v[22:23], v[22:23]
	v_add_f32_e32 v78, v78, v79
	v_add_f32_e32 v79, v124, v125
	v_add_f32_e32 v79, v79, v122
	s_waitcnt vmcnt(2)
	v_pk_mul_f32 v[128:129], v[16:17], v[16:17]
	v_add_f32_e32 v79, v79, v123
	v_pk_mul_f32 v[126:127], v[18:19], v[18:19]
	v_add_f32_e32 v78, v78, v79
	v_add_f32_e32 v79, v128, v129
	v_add_f32_e32 v79, v79, v126
	s_waitcnt vmcnt(1)
	v_pk_mul_f32 v[132:133], v[12:13], v[12:13]
	v_add_f32_e32 v79, v79, v127
	v_pk_mul_f32 v[130:131], v[14:15], v[14:15]
	s_waitcnt vmcnt(0)
	v_pk_mul_f32 v[76:77], v[8:9], v[8:9]
	v_add_f32_e32 v78, v78, v79
	v_add_f32_e32 v79, v132, v133
	v_pk_mul_f32 v[134:135], v[10:11], v[10:11]
	v_add_f32_e32 v79, v79, v130
	v_add_f32_e32 v76, v76, v77
	v_add_f32_e32 v79, v79, v131
	v_add_f32_e32 v76, v76, v134
	v_mov_b32_e32 v80, v7
	v_mov_b32_e32 v81, v3
	v_add_f32_e32 v78, v78, v79
	v_add_f32_e32 v76, v76, v135
	v_pk_fma_f32 v[74:75], v[80:81], v[80:81], v[74:75]
	v_add_f32_e32 v76, v78, v76
	v_add_f32_e32 v74, v76, v74
	v_add_f32_e32 v74, v74, v75
	ds_bpermute_b32 v75, v159, v74
	v_xor_b32_e32 v76, 64, v158
	s_waitcnt lgkmcnt(0)
	v_add_f32_e32 v74, v74, v75
	ds_bpermute_b32 v75, v76, v74
	v_xor_b32_e32 v76, 32, v158
	s_waitcnt lgkmcnt(0)
	v_add_f32_e32 v74, v74, v75
	ds_bpermute_b32 v75, v76, v74
	v_xor_b32_e32 v76, 16, v158
	s_waitcnt lgkmcnt(0)
	v_add_f32_e32 v74, v74, v75
	ds_bpermute_b32 v75, v76, v74
	v_xor_b32_e32 v76, 8, v158
	s_waitcnt lgkmcnt(0)
	v_add_f32_e32 v74, v74, v75
	ds_bpermute_b32 v75, v76, v74
	v_xor_b32_e32 v76, 4, v158
	s_waitcnt lgkmcnt(0)
	v_add_f32_e32 v74, v74, v75
	ds_bpermute_b32 v75, v76, v74
	s_waitcnt lgkmcnt(0)
; __device__ __forceinline__ void rmsnorm_rows(const float* x, const float* g, u16* H, int item, const int wv) {
;     ...
;   const float rstd = 1.0f / sqrtf(ss * (1.0f / D) + EPS);
;   #pragma unroll
;   for (int i = 0; i < 16; ++i) {
;     float4 g4 = ((const float4*)g)[i * 64 + lane];
;     uint2 pk; pk.x = pack2(v[i].x * rstd * g4.x, v[i].y * rstd * g4.y); pk.y = pack2(v[i].z * rstd * g4.z, v[i].w * rstd * g4.w);
;     *(uint2*)(H + (long)row * D + (i * 64 + lane) * 4) = pk;
;   }
	v_add_f32_e32 v74, v74, v75
	v_fmamk_f32 v74, v74, 0x39800000, v64
	v_mul_f32_e32 v75, 0x4f800000, v74
	v_cmp_gt_f32_e32 vcc, s3, v74
	s_nop 1
	v_cndmask_b32_e32 v74, v74, v75, vcc
	v_sqrt_f32_e32 v75, v74
	s_nop 0
	v_add_u32_e32 v76, -1, v75
	v_fma_f32 v77, -v76, v75, v74
	v_cmp_ge_f32_e64 s[0:1], 0, v77
	v_add_u32_e32 v77, 1, v75
	s_nop 0
	v_cndmask_b32_e64 v76, v75, v76, s[0:1]
	v_fma_f32 v75, -v77, v75, v74
	v_cmp_lt_f32_e64 s[0:1], 0, v75
	s_nop 1
	v_cndmask_b32_e64 v75, v76, v77, s[0:1]
	v_mul_f32_e32 v76, 0x37800000, v75
	v_cndmask_b32_e32 v75, v75, v76, vcc
	v_cmp_class_f32_e32 vcc, v74, v65
	s_nop 1
	v_cndmask_b32_e32 v74, v75, v74, vcc
	v_div_scale_f32 v75, s[0:1], v74, v74, 1.0
	v_rcp_f32_e32 v76, v75
	s_lshl_b64 s[0:1], s[4:5], 13
	s_add_u32 s0, s69, s0
	s_addc_u32 s1, s80, s1
	v_fma_f32 v77, -v75, v76, 1.0
	v_fmac_f32_e32 v76, v77, v76
	v_div_scale_f32 v77, vcc, 1.0, v74, 1.0
	v_mul_f32_e32 v78, v77, v76
	v_fma_f32 v79, -v75, v78, v77
	v_fmac_f32_e32 v78, v79, v76
	v_fma_f32 v75, -v75, v78, v77
	v_div_fmas_f32 v75, v75, v76, v78
	v_div_fixup_f32 v74, v75, v74, 1.0
	v_pk_mul_f32 v[60:61], v[60:61], v[74:75] op_sel_hi:[1,0]
	v_pk_mul_f32 v[62:63], v[62:63], v[74:75] op_sel_hi:[1,0]
	v_pk_mul_f32 v[60:61], v[160:161], v[60:61]
	v_pk_mul_f32 v[62:63], v[162:163], v[62:63]
	v_cvt_pk_bf16_f32 v60, v60, v61
	v_cvt_pk_bf16_f32 v61, v62, v63
	global_store_dwordx2 v69, v[60:61], s[0:1]
	v_pk_mul_f32 v[56:57], v[56:57], v[74:75] op_sel_hi:[1,0]
	v_pk_mul_f32 v[58:59], v[58:59], v[74:75] op_sel_hi:[1,0]
	v_or_b32_e32 v70, 0x200, v69
	v_pk_mul_f32 v[52:53], v[52:53], v[74:75] op_sel_hi:[1,0]
	v_pk_mul_f32 v[54:55], v[54:55], v[74:75] op_sel_hi:[1,0]
	v_pk_mul_f32 v[48:49], v[48:49], v[74:75] op_sel_hi:[1,0]
	v_pk_mul_f32 v[50:51], v[50:51], v[74:75] op_sel_hi:[1,0]
	v_pk_mul_f32 v[44:45], v[44:45], v[74:75] op_sel_hi:[1,0]
	v_pk_mul_f32 v[46:47], v[46:47], v[74:75] op_sel_hi:[1,0]
	v_pk_mul_f32 v[40:41], v[40:41], v[74:75] op_sel_hi:[1,0]
	v_pk_mul_f32 v[42:43], v[42:43], v[74:75] op_sel_hi:[1,0]
	v_pk_mul_f32 v[36:37], v[36:37], v[74:75] op_sel_hi:[1,0]
	v_pk_mul_f32 v[38:39], v[38:39], v[74:75] op_sel_hi:[1,0]
	v_pk_mul_f32 v[32:33], v[32:33], v[74:75] op_sel_hi:[1,0]
	v_pk_mul_f32 v[34:35], v[34:35], v[74:75] op_sel_hi:[1,0]
	v_pk_mul_f32 v[28:29], v[28:29], v[74:75] op_sel_hi:[1,0]
	v_pk_mul_f32 v[30:31], v[30:31], v[74:75] op_sel_hi:[1,0]
	v_pk_mul_f32 v[24:25], v[24:25], v[74:75] op_sel_hi:[1,0]
	v_pk_mul_f32 v[26:27], v[26:27], v[74:75] op_sel_hi:[1,0]
	v_pk_mul_f32 v[20:21], v[20:21], v[74:75] op_sel_hi:[1,0]
	v_pk_mul_f32 v[22:23], v[22:23], v[74:75] op_sel_hi:[1,0]
	v_pk_mul_f32 v[16:17], v[16:17], v[74:75] op_sel_hi:[1,0]
	v_pk_mul_f32 v[18:19], v[18:19], v[74:75] op_sel_hi:[1,0]
	v_pk_mul_f32 v[12:13], v[12:13], v[74:75] op_sel_hi:[1,0]
	v_pk_mul_f32 v[14:15], v[14:15], v[74:75] op_sel_hi:[1,0]
	v_pk_mul_f32 v[8:9], v[8:9], v[74:75] op_sel_hi:[1,0]
	v_pk_mul_f32 v[10:11], v[10:11], v[74:75] op_sel_hi:[1,0]
	v_pk_mul_f32 v[4:5], v[4:5], v[74:75] op_sel_hi:[1,0]
	v_pk_mul_f32 v[6:7], v[6:7], v[74:75] op_sel_hi:[1,0]
	v_pk_mul_f32 v[0:1], v[0:1], v[74:75] op_sel_hi:[1,0]
	v_pk_mul_f32 v[2:3], v[2:3], v[74:75] op_sel_hi:[1,0]
	s_add_i32 s8, s8, s91
	s_add_i32 s4, s4, s2
	s_cmpk_gt_i32 s8, 0x7ff
	v_pk_mul_f32 v[56:57], v[164:165], v[56:57]
	v_pk_mul_f32 v[58:59], v[58:59], v[166:167]
	v_cvt_pk_bf16_f32 v56, v56, v57
	v_cvt_pk_bf16_f32 v57, v58, v59
	global_store_dwordx2 v70, v[56:57], s[0:1]
	v_or_b32_e32 v60, 0x400, v69
	v_pk_mul_f32 v[52:53], v[52:53], v[168:169]
	v_pk_mul_f32 v[54:55], v[54:55], v[170:171]
	v_cvt_pk_bf16_f32 v52, v52, v53
	v_cvt_pk_bf16_f32 v53, v54, v55
	global_store_dwordx2 v60, v[52:53], s[0:1]
	v_or_b32_e32 v56, 0x600, v69
	v_pk_mul_f32 v[48:49], v[48:49], v[172:173]
	v_pk_mul_f32 v[50:51], v[50:51], v[174:175]
	v_cvt_pk_bf16_f32 v48, v48, v49
	v_cvt_pk_bf16_f32 v49, v50, v51
	global_store_dwordx2 v56, v[48:49], s[0:1]
	v_lshlrev_b32_e32 v52, 3, v137
	v_pk_mul_f32 v[44:45], v[44:45], v[176:177]
	v_pk_mul_f32 v[46:47], v[46:47], v[178:179]
	v_cvt_pk_bf16_f32 v44, v44, v45
	v_cvt_pk_bf16_f32 v45, v46, v47
	global_store_dwordx2 v52, v[44:45], s[0:1]
	v_lshlrev_b32_e32 v48, 3, v140
	v_pk_mul_f32 v[40:41], v[40:41], v[180:181]
	v_pk_mul_f32 v[42:43], v[42:43], v[182:183]
	v_cvt_pk_bf16_f32 v40, v40, v41
	v_cvt_pk_bf16_f32 v41, v42, v43
	global_store_dwordx2 v48, v[40:41], s[0:1]
	v_lshlrev_b32_e32 v44, 3, v142
	v_pk_mul_f32 v[36:37], v[36:37], v[184:185]
	v_pk_mul_f32 v[38:39], v[38:39], v[186:187]
	v_cvt_pk_bf16_f32 v36, v36, v37
	v_cvt_pk_bf16_f32 v37, v38, v39
	global_store_dwordx2 v44, v[36:37], s[0:1]
	v_lshlrev_b32_e32 v40, 3, v144
	v_pk_mul_f32 v[32:33], v[32:33], v[188:189]
	v_pk_mul_f32 v[34:35], v[34:35], v[190:191]
	v_cvt_pk_bf16_f32 v32, v32, v33
	v_cvt_pk_bf16_f32 v33, v34, v35
	global_store_dwordx2 v40, v[32:33], s[0:1]
	v_lshlrev_b32_e32 v36, 3, v146
	v_pk_mul_f32 v[28:29], v[28:29], v[192:193]
	v_pk_mul_f32 v[30:31], v[30:31], v[194:195]
	v_cvt_pk_bf16_f32 v28, v28, v29
	v_cvt_pk_bf16_f32 v29, v30, v31
	global_store_dwordx2 v36, v[28:29], s[0:1]
	v_lshlrev_b32_e32 v32, 3, v148
	v_pk_mul_f32 v[24:25], v[24:25], v[196:197]
	v_pk_mul_f32 v[26:27], v[26:27], v[198:199]
	v_cvt_pk_bf16_f32 v24, v24, v25
	v_cvt_pk_bf16_f32 v25, v26, v27
	global_store_dwordx2 v32, v[24:25], s[0:1]
	v_lshlrev_b32_e32 v28, 3, v150
	v_pk_mul_f32 v[20:21], v[20:21], v[200:201]
	v_pk_mul_f32 v[22:23], v[22:23], v[202:203]
	v_cvt_pk_bf16_f32 v20, v20, v21
	v_cvt_pk_bf16_f32 v21, v22, v23
	global_store_dwordx2 v28, v[20:21], s[0:1]
	v_lshlrev_b32_e32 v24, 3, v152
	v_pk_mul_f32 v[16:17], v[16:17], v[204:205]
	v_pk_mul_f32 v[18:19], v[18:19], v[206:207]
	v_cvt_pk_bf16_f32 v16, v16, v17
	v_cvt_pk_bf16_f32 v17, v18, v19
	global_store_dwordx2 v24, v[16:17], s[0:1]
	v_lshlrev_b32_e32 v20, 3, v154
	v_pk_mul_f32 v[12:13], v[12:13], v[208:209]
	v_pk_mul_f32 v[14:15], v[14:15], v[210:211]
	v_cvt_pk_bf16_f32 v12, v12, v13
	v_cvt_pk_bf16_f32 v13, v14, v15
	global_store_dwordx2 v20, v[12:13], s[0:1]
	v_lshlrev_b32_e32 v16, 3, v156
	v_pk_mul_f32 v[8:9], v[8:9], v[212:213]
	v_pk_mul_f32 v[10:11], v[10:11], v[214:215]
	v_cvt_pk_bf16_f32 v8, v8, v9
	v_cvt_pk_bf16_f32 v9, v10, v11
	global_store_dwordx2 v16, v[8:9], s[0:1]
	v_lshlrev_b32_e32 v12, 3, v68
	v_pk_mul_f32 v[4:5], v[4:5], v[216:217]
	v_pk_mul_f32 v[6:7], v[6:7], v[218:219]
	v_cvt_pk_bf16_f32 v4, v4, v5
	v_cvt_pk_bf16_f32 v5, v6, v7
	global_store_dwordx2 v12, v[4:5], s[0:1]
	v_lshlrev_b32_e32 v8, 3, v66
	v_pk_mul_f32 v[0:1], v[0:1], v[220:221]
	v_pk_mul_f32 v[2:3], v[2:3], v[222:223]
	v_cvt_pk_bf16_f32 v0, v0, v1
	v_cvt_pk_bf16_f32 v1, v2, v3
	global_store_dwordx2 v8, v[0:1], s[0:1]
	s_cbranch_scc0 .LBB0_517

; __device__ __forceinline__ float bf_lo(u32 v) { return __uint_as_float(v << 16); }
; __device__ __forceinline__ float bf_hi(u32 v) { return __uint_as_float(v & 0xffff0000u); }
; __device__ __forceinline__ void ret_final_item(const Params& p, int item, const int wv) {
;   const int tid = opaque_tid(wv);
;   const int wid = wv, lane = tid & 63;
;   const int pair = item * 8 + wid;
;   const int tok = pair >> 3, h = pair & 7;
;   const u16* OD = (const u16*)(p.ws + OFF_H) + (long)tok * 2048 + h * 256 + lane * 4;
;   u16* Y = (u16*)(p.ws + OFF_PB1) + (long)tok * LD1 + 8192 + 2048 + h * 256 + lane * 4;
;   const uint2 ov = *(const uint2*)OD;
;   const float o0 = bf_lo(ov.x), o1 = bf_hi(ov.x), o2 = bf_lo(ov.y), o3 = bf_hi(ov.y);
;   float ss = o0 * o0 + o1 * o1 + o2 * o2 + o3 * o3;
;   #pragma unroll
;   for (int d = 32; d >= 1; d >>= 1) ss += sx(ss, d, lane);
;   const float rstd = 1.0f / sqrtf(ss * (1.0f / 256.f) + EPS);
;   const float4 g = *(const float4*)(p.rn_g + h * 256 + lane * 4);
;   const uint2 gv = *(const uint2*)Y;
; __global__ void __launch_bounds__(512) fwd_megakernel(Params p) {
;     ...
;   for (int it = blockIdx.x; it < 16384; it += gridDim.x) ret_final_item(p, it, wv);
.LBB0_761:
	s_or_b64 exec, exec, s[0:1]
	s_cmpk_gt_i32 s83, 0x3fff
	s_barrier
	s_cbranch_scc1 .LBB0_764
	v_readlane_b32 s9, v255, 10
	s_lshl_b32 s0, s9, 8
	s_and_b32 s0, s0, 0x700
	s_lshl_b32 s1, s0, 1
	s_add_u32 s2, s69, s1
	s_addc_u32 s8, s80, 0
	s_lshl_b32 s1, s0, 2
	s_add_u32 s4, s78, s1
	s_addc_u32 s5, s79, 0
	s_lshl_b32 s1, s83, 3
	s_add_i32 s9, s9, s1
	s_lshl_b32 s10, s91, 3
	v_mov_b32_e32 v1, 0
	s_movk_i32 s11, 0x80
	v_bfrev_b32_e32 v2, 0.5
	s_lshl_b32 s12, s0, 1
	s_mov_b32 s13, 0x1ac05000
	v_mov_b32_e32 v3, 0x358637bd
	s_mov_b32 s14, 0xf800000
	s_waitcnt vmcnt(14)
	v_mov_b32_e32 v4, 0x260
	s_mov_b32 s15, s83
	v_mbcnt_lo_u32_b32 v28, -1, 0
	v_mbcnt_hi_u32_b32 v28, -1, v28
	s_nop 0
	v_lshlrev_b32_e32 v28, 2, v28
	v_and_b32_e32 v31, 0xfc, v28
	v_bitop3_b32 v32, v28, s11, v2 bitop3:0x6c
	v_bitop3_b32 v33, v28, 64, v2 bitop3:0x6c
	v_bitop3_b32 v34, v28, 32, v2 bitop3:0x6c
	v_bitop3_b32 v35, v28, 16, v2 bitop3:0x6c
	v_bitop3_b32 v36, v28, 8, v2 bitop3:0x6c
	v_bitop3_b32 v37, v28, 4, v2 bitop3:0x6c
	v_lshlrev_b32_e32 v28, 1, v31
	v_mov_b32_e32 v29, 0
	v_lshlrev_b32_e32 v30, 2, v31
	global_load_dwordx4 v[40:43], v30, s[4:5]
.Lrf_check:
	s_mul_i32 s16, s91, 7
	s_add_i32 s16, s16, s15
	s_cmpk_gt_i32 s16, 0x3fff
	s_cbranch_scc1 .Lrf_tail
	s_ashr_i32 s0, s9, 3
	s_ashr_i32 s1, s0, 31
	s_mul_hi_i32 s16, s0, 0x6000
	s_mul_i32 s17, s0, 0x6000
	s_lshl_b64 s[0:1], s[0:1], 12
	s_add_u32 s0, s2, s0
	s_addc_u32 s1, s8, s1
	global_load_dwordx2 v[48:49], v28, s[0:1]
	s_add_u32 s0, s96, s17
	s_addc_u32 s1, s97, s16
	s_add_u32 s0, s0, s12
	s_addc_u32 s1, s1, 0
	s_add_u32 s0, s0, s13
	s_addc_u32 s1, s1, 0
	v_lshl_add_u64 v[52:53], s[0:1], 0, v[28:29]
	s_add_i32 s9, s9, s10
	s_add_i32 s15, s15, s91
	s_nop 0
	global_load_dwordx2 v[50:51], v[52:53], off offset:256
	s_ashr_i32 s0, s9, 3
	s_ashr_i32 s1, s0, 31
	s_mul_hi_i32 s16, s0, 0x6000
	s_mul_i32 s17, s0, 0x6000
	s_lshl_b64 s[0:1], s[0:1], 12
	s_add_u32 s0, s2, s0
	s_addc_u32 s1, s8, s1
	global_load_dwordx2 v[72:73], v28, s[0:1]
	s_add_u32 s0, s96, s17
	s_addc_u32 s1, s97, s16
	s_add_u32 s0, s0, s12
	s_addc_u32 s1, s1, 0
	s_add_u32 s0, s0, s13
	s_addc_u32 s1, s1, 0
	v_lshl_add_u64 v[76:77], s[0:1], 0, v[28:29]
	s_add_i32 s9, s9, s10
	s_add_i32 s15, s15, s91
	s_nop 0
	global_load_dwordx2 v[74:75], v[76:77], off offset:256
	s_ashr_i32 s0, s9, 3
	s_ashr_i32 s1, s0, 31
	s_mul_hi_i32 s16, s0, 0x6000
	s_mul_i32 s17, s0, 0x6000
	s_lshl_b64 s[0:1], s[0:1], 12
	s_add_u32 s0, s2, s0
	s_addc_u32 s1, s8, s1
	global_load_dwordx2 v[96:97], v28, s[0:1]
	s_add_u32 s0, s96, s17
	s_addc_u32 s1, s97, s16
	s_add_u32 s0, s0, s12
	s_addc_u32 s1, s1, 0
	s_add_u32 s0, s0, s13
	s_addc_u32 s1, s1, 0
	v_lshl_add_u64 v[100:101], s[0:1], 0, v[28:29]
	s_add_i32 s9, s9, s10
	s_add_i32 s15, s15, s91
	s_nop 0
	global_load_dwordx2 v[98:99], v[100:101], off offset:256
	s_ashr_i32 s0, s9, 3
	s_ashr_i32 s1, s0, 31
	s_mul_hi_i32 s16, s0, 0x6000
	s_mul_i32 s17, s0, 0x6000
	s_lshl_b64 s[0:1], s[0:1], 12
	s_add_u32 s0, s2, s0
	s_addc_u32 s1, s8, s1
	global_load_dwordx2 v[120:121], v28, s[0:1]
	s_add_u32 s0, s96, s17
	s_addc_u32 s1, s97, s16
	s_add_u32 s0, s0, s12
	s_addc_u32 s1, s1, 0
	s_add_u32 s0, s0, s13
	s_addc_u32 s1, s1, 0
	v_lshl_add_u64 v[124:125], s[0:1], 0, v[28:29]
	s_add_i32 s9, s9, s10
	s_add_i32 s15, s15, s91
	s_nop 0
	global_load_dwordx2 v[122:123], v[124:125], off offset:256
	s_ashr_i32 s0, s9, 3
	s_ashr_i32 s1, s0, 31
	s_mul_hi_i32 s16, s0, 0x6000
	s_mul_i32 s17, s0, 0x6000
	s_lshl_b64 s[0:1], s[0:1], 12
	s_add_u32 s0, s2, s0
	s_addc_u32 s1, s8, s1
	global_load_dwordx2 v[144:145], v28, s[0:1]
	s_add_u32 s0, s96, s17
	s_addc_u32 s1, s97, s16
	s_add_u32 s0, s0, s12
	s_addc_u32 s1, s1, 0
	s_add_u32 s0, s0, s13
	s_addc_u32 s1, s1, 0
	v_lshl_add_u64 v[148:149], s[0:1], 0, v[28:29]
	s_add_i32 s9, s9, s10
	s_add_i32 s15, s15, s91
	s_nop 0
	global_load_dwordx2 v[146:147], v[148:149], off offset:256
	s_ashr_i32 s0, s9, 3
	s_ashr_i32 s1, s0, 31
	s_mul_hi_i32 s16, s0, 0x6000
	s_mul_i32 s17, s0, 0x6000
	s_lshl_b64 s[0:1], s[0:1], 12
	s_add_u32 s0, s2, s0
	s_addc_u32 s1, s8, s1
	global_load_dwordx2 v[168:169], v28, s[0:1]
	s_add_u32 s0, s96, s17
	s_addc_u32 s1, s97, s16
	s_add_u32 s0, s0, s12
	s_addc_u32 s1, s1, 0
	s_add_u32 s0, s0, s13
	s_addc_u32 s1, s1, 0
	v_lshl_add_u64 v[172:173], s[0:1], 0, v[28:29]
	s_add_i32 s9, s9, s10
	s_add_i32 s15, s15, s91
	s_nop 0
	global_load_dwordx2 v[170:171], v[172:173], off offset:256
	s_ashr_i32 s0, s9, 3
	s_ashr_i32 s1, s0, 31
	s_mul_hi_i32 s16, s0, 0x6000
	s_mul_i32 s17, s0, 0x6000
	s_lshl_b64 s[0:1], s[0:1], 12
	s_add_u32 s0, s2, s0
	s_addc_u32 s1, s8, s1
	global_load_dwordx2 v[192:193], v28, s[0:1]
	s_add_u32 s0, s96, s17
	s_addc_u32 s1, s97, s16
	s_add_u32 s0, s0, s12
	s_addc_u32 s1, s1, 0
	s_add_u32 s0, s0, s13
	s_addc_u32 s1, s1, 0
	v_lshl_add_u64 v[196:197], s[0:1], 0, v[28:29]
	s_add_i32 s9, s9, s10
	s_add_i32 s15, s15, s91
	s_nop 0
	global_load_dwordx2 v[194:195], v[196:197], off offset:256
	s_ashr_i32 s0, s9, 3
	s_ashr_i32 s1, s0, 31
	s_mul_hi_i32 s16, s0, 0x6000
	s_mul_i32 s17, s0, 0x6000
	s_lshl_b64 s[0:1], s[0:1], 12
	s_add_u32 s0, s2, s0
	s_addc_u32 s1, s8, s1
	global_load_dwordx2 v[216:217], v28, s[0:1]
	s_add_u32 s0, s96, s17
	s_addc_u32 s1, s97, s16
	s_add_u32 s0, s0, s12
	s_addc_u32 s1, s1, 0
	s_add_u32 s0, s0, s13
	s_addc_u32 s1, s1, 0
	v_lshl_add_u64 v[220:221], s[0:1], 0, v[28:29]
	s_add_i32 s9, s9, s10
	s_add_i32 s15, s15, s91
	s_nop 0
	global_load_dwordx2 v[218:219], v[220:221], off offset:256
	s_waitcnt vmcnt(0)
; __device__ __forceinline__ float bf_lo(u32 v) { return __uint_as_float(v << 16); }
; __device__ __forceinline__ float bf_hi(u32 v) { return __uint_as_float(v & 0xffff0000u); }
; __device__ __forceinline__ void ret_final_item(const Params& p, int item, const int wv) {
;     ...
;   const uint2 ov = *(const uint2*)OD;
;   const float o0 = bf_lo(ov.x), o1 = bf_hi(ov.x), o2 = bf_lo(ov.y), o3 = bf_hi(ov.y);
;   float ss = o0 * o0 + o1 * o1 + o2 * o2 + o3 * o3;
;   #pragma unroll
;   for (int d = 32; d >= 1; d >>= 1) ss += sx(ss, d, lane);
	v_lshlrev_b32_e32 v54, 16, v48
	v_and_b32_e32 v55, 0xffff0000, v48
	v_lshlrev_b32_e32 v56, 16, v49
	v_and_b32_e32 v57, 0xffff0000, v49
	v_pk_mul_f32 v[60:61], v[54:55], v[54:55]
	v_pk_mul_f32 v[62:63], v[56:57], v[56:57]
	v_lshlrev_b32_e32 v68, 16, v50
	v_and_b32_e32 v69, 0xffff0000, v50
	v_lshlrev_b32_e32 v70, 16, v51
	v_and_b32_e32 v71, 0xffff0000, v51
	v_add_f32_e32 v58, v60, v61
	v_add_f32_e32 v58, v58, v62
	v_add_f32_e32 v58, v63, v58
	v_lshlrev_b32_e32 v78, 16, v72
	v_and_b32_e32 v79, 0xffff0000, v72
	v_lshlrev_b32_e32 v80, 16, v73
	v_and_b32_e32 v81, 0xffff0000, v73
	v_pk_mul_f32 v[84:85], v[78:79], v[78:79]
	v_pk_mul_f32 v[86:87], v[80:81], v[80:81]
	v_lshlrev_b32_e32 v92, 16, v74
	v_and_b32_e32 v93, 0xffff0000, v74
	v_lshlrev_b32_e32 v94, 16, v75
	v_and_b32_e32 v95, 0xffff0000, v75
	v_add_f32_e32 v82, v84, v85
	v_add_f32_e32 v82, v82, v86
	v_add_f32_e32 v82, v87, v82
	v_lshlrev_b32_e32 v102, 16, v96
	v_and_b32_e32 v103, 0xffff0000, v96
	v_lshlrev_b32_e32 v104, 16, v97
	v_and_b32_e32 v105, 0xffff0000, v97
	v_pk_mul_f32 v[108:109], v[102:103], v[102:103]
	v_pk_mul_f32 v[110:111], v[104:105], v[104:105]
	v_lshlrev_b32_e32 v116, 16, v98
	v_and_b32_e32 v117, 0xffff0000, v98
	v_lshlrev_b32_e32 v118, 16, v99
	v_and_b32_e32 v119, 0xffff0000, v99
	v_add_f32_e32 v106, v108, v109
	v_add_f32_e32 v106, v106, v110
	v_add_f32_e32 v106, v111, v106
	v_lshlrev_b32_e32 v126, 16, v120
	v_and_b32_e32 v127, 0xffff0000, v120
	v_lshlrev_b32_e32 v128, 16, v121
	v_and_b32_e32 v129, 0xffff0000, v121
	v_pk_mul_f32 v[132:133], v[126:127], v[126:127]
	v_pk_mul_f32 v[134:135], v[128:129], v[128:129]
	v_lshlrev_b32_e32 v140, 16, v122
	v_and_b32_e32 v141, 0xffff0000, v122
	v_lshlrev_b32_e32 v142, 16, v123
	v_and_b32_e32 v143, 0xffff0000, v123
	v_add_f32_e32 v130, v132, v133
	v_add_f32_e32 v130, v130, v134
	v_add_f32_e32 v130, v135, v130
	v_lshlrev_b32_e32 v150, 16, v144
	v_and_b32_e32 v151, 0xffff0000, v144
	v_lshlrev_b32_e32 v152, 16, v145
	v_and_b32_e32 v153, 0xffff0000, v145
	v_pk_mul_f32 v[156:157], v[150:151], v[150:151]
	v_pk_mul_f32 v[158:159], v[152:153], v[152:153]
	v_lshlrev_b32_e32 v164, 16, v146
	v_and_b32_e32 v165, 0xffff0000, v146
	v_lshlrev_b32_e32 v166, 16, v147
	v_and_b32_e32 v167, 0xffff0000, v147
	v_add_f32_e32 v154, v156, v157
	v_add_f32_e32 v154, v154, v158
	v_add_f32_e32 v154, v159, v154
	v_lshlrev_b32_e32 v174, 16, v168
	v_and_b32_e32 v175, 0xffff0000, v168
	v_lshlrev_b32_e32 v176, 16, v169
	v_and_b32_e32 v177, 0xffff0000, v169
	v_pk_mul_f32 v[180:181], v[174:175], v[174:175]
	v_pk_mul_f32 v[182:183], v[176:177], v[176:177]
	v_lshlrev_b32_e32 v188, 16, v170
	v_and_b32_e32 v189, 0xffff0000, v170
	v_lshlrev_b32_e32 v190, 16, v171
	v_and_b32_e32 v191, 0xffff0000, v171
	v_add_f32_e32 v178, v180, v181
	v_add_f32_e32 v178, v178, v182
	v_add_f32_e32 v178, v183, v178
	v_lshlrev_b32_e32 v198, 16, v192
	v_and_b32_e32 v199, 0xffff0000, v192
	v_lshlrev_b32_e32 v200, 16, v193
	v_and_b32_e32 v201, 0xffff0000, v193
	v_pk_mul_f32 v[204:205], v[198:199], v[198:199]
	v_pk_mul_f32 v[206:207], v[200:201], v[200:201]
	v_lshlrev_b32_e32 v212, 16, v194
	v_and_b32_e32 v213, 0xffff0000, v194
	v_lshlrev_b32_e32 v214, 16, v195
	v_and_b32_e32 v215, 0xffff0000, v195
	v_add_f32_e32 v202, v204, v205
	v_add_f32_e32 v202, v202, v206
	v_add_f32_e32 v202, v207, v202
	v_lshlrev_b32_e32 v222, 16, v216
	v_and_b32_e32 v223, 0xffff0000, v216
	v_lshlrev_b32_e32 v224, 16, v217
	v_and_b32_e32 v225, 0xffff0000, v217
	v_pk_mul_f32 v[228:229], v[222:223], v[222:223]
	v_pk_mul_f32 v[230:231], v[224:225], v[224:225]
	v_lshlrev_b32_e32 v236, 16, v218
	v_and_b32_e32 v237, 0xffff0000, v218
	v_lshlrev_b32_e32 v238, 16, v219
	v_and_b32_e32 v239, 0xffff0000, v219
	v_add_f32_e32 v226, v228, v229
	v_add_f32_e32 v226, v226, v230
	v_add_f32_e32 v226, v231, v226
	ds_bpermute_b32 v64, v32, v58
	ds_bpermute_b32 v88, v32, v82
	ds_bpermute_b32 v112, v32, v106
	ds_bpermute_b32 v136, v32, v130
	ds_bpermute_b32 v160, v32, v154
	ds_bpermute_b32 v184, v32, v178
	ds_bpermute_b32 v208, v32, v202
	ds_bpermute_b32 v232, v32, v226
	s_waitcnt lgkmcnt(7)
	v_add_f32_e32 v58, v58, v64
	s_waitcnt lgkmcnt(6)
	v_add_f32_e32 v82, v82, v88
	s_waitcnt lgkmcnt(5)
	v_add_f32_e32 v106, v106, v112
	s_waitcnt lgkmcnt(4)
	v_add_f32_e32 v130, v130, v136
	s_waitcnt lgkmcnt(3)
	v_add_f32_e32 v154, v154, v160
	s_waitcnt lgkmcnt(2)
	v_add_f32_e32 v178, v178, v184
	s_waitcnt lgkmcnt(1)
	v_add_f32_e32 v202, v202, v208
	s_waitcnt lgkmcnt(0)
	v_add_f32_e32 v226, v226, v232
	ds_bpermute_b32 v64, v33, v58
	ds_bpermute_b32 v88, v33, v82
	ds_bpermute_b32 v112, v33, v106
	ds_bpermute_b32 v136, v33, v130
	ds_bpermute_b32 v160, v33, v154
	ds_bpermute_b32 v184, v33, v178
	ds_bpermute_b32 v208, v33, v202
	ds_bpermute_b32 v232, v33, v226
	s_waitcnt lgkmcnt(7)
	v_add_f32_e32 v58, v58, v64
	s_waitcnt lgkmcnt(6)
	v_add_f32_e32 v82, v82, v88
	s_waitcnt lgkmcnt(5)
	v_add_f32_e32 v106, v106, v112
	s_waitcnt lgkmcnt(4)
	v_add_f32_e32 v130, v130, v136
	s_waitcnt lgkmcnt(3)
	v_add_f32_e32 v154, v154, v160
	s_waitcnt lgkmcnt(2)
	v_add_f32_e32 v178, v178, v184
	s_waitcnt lgkmcnt(1)
	v_add_f32_e32 v202, v202, v208
	s_waitcnt lgkmcnt(0)
	v_add_f32_e32 v226, v226, v232
	ds_bpermute_b32 v64, v34, v58
	ds_bpermute_b32 v88, v34, v82
	ds_bpermute_b32 v112, v34, v106
	ds_bpermute_b32 v136, v34, v130
	ds_bpermute_b32 v160, v34, v154
	ds_bpermute_b32 v184, v34, v178
	ds_bpermute_b32 v208, v34, v202
	ds_bpermute_b32 v232, v34, v226
	s_waitcnt lgkmcnt(7)
	v_add_f32_e32 v58, v58, v64
	s_waitcnt lgkmcnt(6)
	v_add_f32_e32 v82, v82, v88
	s_waitcnt lgkmcnt(5)
	v_add_f32_e32 v106, v106, v112
	s_waitcnt lgkmcnt(4)
	v_add_f32_e32 v130, v130, v136
	s_waitcnt lgkmcnt(3)
; __device__ __forceinline__ float bf_lo(u32 v) { return __uint_as_float(v << 16); }
; __device__ __forceinline__ float bf_hi(u32 v) { return __uint_as_float(v & 0xffff0000u); }
; __device__ __forceinline__ void ret_final_item(const Params& p, int item, const int wv) {
;     ...
;   for (int d = 32; d >= 1; d >>= 1) ss += sx(ss, d, lane);
;   const float rstd = 1.0f / sqrtf(ss * (1.0f / 256.f) + EPS);
;   const float4 g = *(const float4*)(p.rn_g + h * 256 + lane * 4);
;   const uint2 gv = *(const uint2*)Y;
;   uint2 pk;
;   pk.x = pack2(o0 * rstd * g.x * bf_lo(gv.x), o1 * rstd * g.y * bf_hi(gv.x));
;   pk.y = pack2(o2 * rstd * g.z * bf_lo(gv.y), o3 * rstd * g.w * bf_hi(gv.y));
;   *(uint2*)Y = pk;
	v_add_f32_e32 v154, v154, v160
	s_waitcnt lgkmcnt(2)
	v_add_f32_e32 v178, v178, v184
	s_waitcnt lgkmcnt(1)
	v_add_f32_e32 v202, v202, v208
	s_waitcnt lgkmcnt(0)
	v_add_f32_e32 v226, v226, v232
	ds_bpermute_b32 v64, v35, v58
	ds_bpermute_b32 v88, v35, v82
	ds_bpermute_b32 v112, v35, v106
	ds_bpermute_b32 v136, v35, v130
	ds_bpermute_b32 v160, v35, v154
	ds_bpermute_b32 v184, v35, v178
	ds_bpermute_b32 v208, v35, v202
	ds_bpermute_b32 v232, v35, v226
	s_waitcnt lgkmcnt(7)
	v_add_f32_e32 v58, v58, v64
	s_waitcnt lgkmcnt(6)
	v_add_f32_e32 v82, v82, v88
	s_waitcnt lgkmcnt(5)
	v_add_f32_e32 v106, v106, v112
	s_waitcnt lgkmcnt(4)
	v_add_f32_e32 v130, v130, v136
	s_waitcnt lgkmcnt(3)
	v_add_f32_e32 v154, v154, v160
	s_waitcnt lgkmcnt(2)
	v_add_f32_e32 v178, v178, v184
	s_waitcnt lgkmcnt(1)
	v_add_f32_e32 v202, v202, v208
	s_waitcnt lgkmcnt(0)
	v_add_f32_e32 v226, v226, v232
	ds_bpermute_b32 v64, v36, v58
	ds_bpermute_b32 v88, v36, v82
	ds_bpermute_b32 v112, v36, v106
	ds_bpermute_b32 v136, v36, v130
	ds_bpermute_b32 v160, v36, v154
	ds_bpermute_b32 v184, v36, v178
	ds_bpermute_b32 v208, v36, v202
	ds_bpermute_b32 v232, v36, v226
	s_waitcnt lgkmcnt(7)
	v_add_f32_e32 v58, v58, v64
	s_waitcnt lgkmcnt(6)
	v_add_f32_e32 v82, v82, v88
	s_waitcnt lgkmcnt(5)
	v_add_f32_e32 v106, v106, v112
	s_waitcnt lgkmcnt(4)
	v_add_f32_e32 v130, v130, v136
	s_waitcnt lgkmcnt(3)
	v_add_f32_e32 v154, v154, v160
	s_waitcnt lgkmcnt(2)
	v_add_f32_e32 v178, v178, v184
	s_waitcnt lgkmcnt(1)
	v_add_f32_e32 v202, v202, v208
	s_waitcnt lgkmcnt(0)
	v_add_f32_e32 v226, v226, v232
	ds_bpermute_b32 v64, v37, v58
	ds_bpermute_b32 v88, v37, v82
	ds_bpermute_b32 v112, v37, v106
	ds_bpermute_b32 v136, v37, v130
	ds_bpermute_b32 v160, v37, v154
	ds_bpermute_b32 v184, v37, v178
	ds_bpermute_b32 v208, v37, v202
	ds_bpermute_b32 v232, v37, v226
	s_waitcnt lgkmcnt(7)
	v_add_f32_e32 v58, v58, v64
	s_waitcnt lgkmcnt(6)
	v_add_f32_e32 v82, v82, v88
	s_waitcnt lgkmcnt(5)
	v_add_f32_e32 v106, v106, v112
	s_waitcnt lgkmcnt(4)
	v_add_f32_e32 v130, v130, v136
	s_waitcnt lgkmcnt(3)
	v_add_f32_e32 v154, v154, v160
	s_waitcnt lgkmcnt(2)
	v_add_f32_e32 v178, v178, v184
	s_waitcnt lgkmcnt(1)
	v_add_f32_e32 v202, v202, v208
	s_waitcnt lgkmcnt(0)
	v_add_f32_e32 v226, v226, v232
	v_fmamk_f32 v58, v58, 0x3b800000, v3
	v_mul_f32_e32 v64, 0x4f800000, v58
	v_cmp_gt_f32_e32 vcc, s14, v58
	s_nop 1
	v_cndmask_b32_e32 v58, v58, v64, vcc
	v_sqrt_f32_e32 v64, v58
	s_nop 0
	v_add_u32_e32 v65, -1, v64
	v_add_u32_e32 v66, 1, v64
	v_fma_f32 v67, -v65, v64, v58
	v_fma_f32 v59, -v66, v64, v58
	v_cmp_ge_f32_e64 s[0:1], 0, v67
	s_nop 1
	v_cndmask_b32_e64 v64, v64, v65, s[0:1]
	v_cmp_lt_f32_e64 s[0:1], 0, v59
	s_nop 1
	v_cndmask_b32_e64 v64, v64, v66, s[0:1]
	v_mul_f32_e32 v65, 0x37800000, v64
	v_cndmask_b32_e32 v64, v64, v65, vcc
	v_cmp_class_f32_e32 vcc, v58, v4
	s_nop 1
	v_cndmask_b32_e32 v58, v64, v58, vcc
	v_div_scale_f32 v64, s[0:1], v58, v58, 1.0
	v_rcp_f32_e32 v66, v64
	v_div_scale_f32 v65, vcc, 1.0, v58, 1.0
	v_fma_f32 v67, -v64, v66, 1.0
	v_fmac_f32_e32 v66, v67, v66
	v_mul_f32_e32 v67, v65, v66
	v_fma_f32 v59, -v64, v67, v65
	v_fmac_f32_e32 v67, v59, v66
	v_fma_f32 v64, -v64, v67, v65
	v_div_fmas_f32 v64, v64, v66, v67
	v_div_fixup_f32 v58, v64, v58, 1.0
	v_pk_mul_f32 v[54:55], v[58:59], v[54:55] op_sel_hi:[0,1]
	v_pk_mul_f32 v[56:57], v[58:59], v[56:57] op_sel_hi:[0,1]
	v_pk_mul_f32 v[60:61], v[40:41], v[54:55]
	v_pk_mul_f32 v[62:63], v[42:43], v[56:57]
	v_pk_mul_f32 v[60:61], v[60:61], v[68:69]
	v_pk_mul_f32 v[62:63], v[62:63], v[70:71]
	v_cvt_pk_bf16_f32 v60, v60, v61
	v_cvt_pk_bf16_f32 v61, v62, v63
	global_store_dwordx2 v[52:53], v[60:61], off offset:256
	v_fmamk_f32 v82, v82, 0x3b800000, v3
	v_mul_f32_e32 v88, 0x4f800000, v82
	v_cmp_gt_f32_e32 vcc, s14, v82
	s_nop 1
	v_cndmask_b32_e32 v82, v82, v88, vcc
	v_sqrt_f32_e32 v88, v82
	s_nop 0
	v_add_u32_e32 v89, -1, v88
	v_add_u32_e32 v90, 1, v88
	v_fma_f32 v91, -v89, v88, v82
	v_fma_f32 v83, -v90, v88, v82
	v_cmp_ge_f32_e64 s[0:1], 0, v91
	s_nop 1
	v_cndmask_b32_e64 v88, v88, v89, s[0:1]
	v_cmp_lt_f32_e64 s[0:1], 0, v83
	s_nop 1
	v_cndmask_b32_e64 v88, v88, v90, s[0:1]
	v_mul_f32_e32 v89, 0x37800000, v88
	v_cndmask_b32_e32 v88, v88, v89, vcc
	v_cmp_class_f32_e32 vcc, v82, v4
	s_nop 1
	v_cndmask_b32_e32 v82, v88, v82, vcc
	v_div_scale_f32 v88, s[0:1], v82, v82, 1.0
	v_rcp_f32_e32 v90, v88
	v_div_scale_f32 v89, vcc, 1.0, v82, 1.0
	v_fma_f32 v91, -v88, v90, 1.0
	v_fmac_f32_e32 v90, v91, v90
	v_mul_f32_e32 v91, v89, v90
	v_fma_f32 v83, -v88, v91, v89
	v_fmac_f32_e32 v91, v83, v90
	v_fma_f32 v88, -v88, v91, v89
	v_div_fmas_f32 v88, v88, v90, v91
	v_div_fixup_f32 v82, v88, v82, 1.0
	v_pk_mul_f32 v[78:79], v[82:83], v[78:79] op_sel_hi:[0,1]
	v_pk_mul_f32 v[80:81], v[82:83], v[80:81] op_sel_hi:[0,1]
	v_pk_mul_f32 v[84:85], v[40:41], v[78:79]
	v_pk_mul_f32 v[86:87], v[42:43], v[80:81]
	v_pk_mul_f32 v[84:85], v[84:85], v[92:93]
	v_pk_mul_f32 v[86:87], v[86:87], v[94:95]
	v_cvt_pk_bf16_f32 v84, v84, v85
	v_cvt_pk_bf16_f32 v85, v86, v87
	global_store_dwordx2 v[76:77], v[84:85], off offset:256
	v_fmamk_f32 v106, v106, 0x3b800000, v3
	v_mul_f32_e32 v112, 0x4f800000, v106
	v_cmp_gt_f32_e32 vcc, s14, v106
	s_nop 1
	v_cndmask_b32_e32 v106, v106, v112, vcc
	v_sqrt_f32_e32 v112, v106
	s_nop 0
	v_add_u32_e32 v113, -1, v112
	v_add_u32_e32 v114, 1, v112
	v_fma_f32 v115, -v113, v112, v106
	v_fma_f32 v107, -v114, v112, v106
	v_cmp_ge_f32_e64 s[0:1], 0, v115
	s_nop 1
	v_cndmask_b32_e64 v112, v112, v113, s[0:1]
	v_cmp_lt_f32_e64 s[0:1], 0, v107
	s_nop 1
	v_cndmask_b32_e64 v112, v112, v114, s[0:1]
	v_mul_f32_e32 v113, 0x37800000, v112
	v_cndmask_b32_e32 v112, v112, v113, vcc
; __device__ __forceinline__ float bf_lo(u32 v) { return __uint_as_float(v << 16); }
; __device__ __forceinline__ float bf_hi(u32 v) { return __uint_as_float(v & 0xffff0000u); }
; __device__ __forceinline__ void ret_final_item(const Params& p, int item, const int wv) {
;     ...
;   const float rstd = 1.0f / sqrtf(ss * (1.0f / 256.f) + EPS);
;   const float4 g = *(const float4*)(p.rn_g + h * 256 + lane * 4);
;   const uint2 gv = *(const uint2*)Y;
;   uint2 pk;
;   pk.x = pack2(o0 * rstd * g.x * bf_lo(gv.x), o1 * rstd * g.y * bf_hi(gv.x));
;   pk.y = pack2(o2 * rstd * g.z * bf_lo(gv.y), o3 * rstd * g.w * bf_hi(gv.y));
;   *(uint2*)Y = pk;
	v_cmp_class_f32_e32 vcc, v106, v4
	s_nop 1
	v_cndmask_b32_e32 v106, v112, v106, vcc
	v_div_scale_f32 v112, s[0:1], v106, v106, 1.0
	v_rcp_f32_e32 v114, v112
	v_div_scale_f32 v113, vcc, 1.0, v106, 1.0
	v_fma_f32 v115, -v112, v114, 1.0
	v_fmac_f32_e32 v114, v115, v114
	v_mul_f32_e32 v115, v113, v114
	v_fma_f32 v107, -v112, v115, v113
	v_fmac_f32_e32 v115, v107, v114
	v_fma_f32 v112, -v112, v115, v113
	v_div_fmas_f32 v112, v112, v114, v115
	v_div_fixup_f32 v106, v112, v106, 1.0
	v_pk_mul_f32 v[102:103], v[106:107], v[102:103] op_sel_hi:[0,1]
	v_pk_mul_f32 v[104:105], v[106:107], v[104:105] op_sel_hi:[0,1]
	v_pk_mul_f32 v[108:109], v[40:41], v[102:103]
	v_pk_mul_f32 v[110:111], v[42:43], v[104:105]
	v_pk_mul_f32 v[108:109], v[108:109], v[116:117]
	v_pk_mul_f32 v[110:111], v[110:111], v[118:119]
	v_cvt_pk_bf16_f32 v108, v108, v109
	v_cvt_pk_bf16_f32 v109, v110, v111
	global_store_dwordx2 v[100:101], v[108:109], off offset:256
	v_fmamk_f32 v130, v130, 0x3b800000, v3
	v_mul_f32_e32 v136, 0x4f800000, v130
	v_cmp_gt_f32_e32 vcc, s14, v130
	s_nop 1
	v_cndmask_b32_e32 v130, v130, v136, vcc
	v_sqrt_f32_e32 v136, v130
	s_nop 0
	v_add_u32_e32 v137, -1, v136
	v_add_u32_e32 v138, 1, v136
	v_fma_f32 v139, -v137, v136, v130
	v_fma_f32 v131, -v138, v136, v130
	v_cmp_ge_f32_e64 s[0:1], 0, v139
	s_nop 1
	v_cndmask_b32_e64 v136, v136, v137, s[0:1]
	v_cmp_lt_f32_e64 s[0:1], 0, v131
	s_nop 1
	v_cndmask_b32_e64 v136, v136, v138, s[0:1]
	v_mul_f32_e32 v137, 0x37800000, v136
	v_cndmask_b32_e32 v136, v136, v137, vcc
	v_cmp_class_f32_e32 vcc, v130, v4
	s_nop 1
	v_cndmask_b32_e32 v130, v136, v130, vcc
	v_div_scale_f32 v136, s[0:1], v130, v130, 1.0
	v_rcp_f32_e32 v138, v136
	v_div_scale_f32 v137, vcc, 1.0, v130, 1.0
	v_fma_f32 v139, -v136, v138, 1.0
	v_fmac_f32_e32 v138, v139, v138
	v_mul_f32_e32 v139, v137, v138
	v_fma_f32 v131, -v136, v139, v137
	v_fmac_f32_e32 v139, v131, v138
	v_fma_f32 v136, -v136, v139, v137
	v_div_fmas_f32 v136, v136, v138, v139
	v_div_fixup_f32 v130, v136, v130, 1.0
	v_pk_mul_f32 v[126:127], v[130:131], v[126:127] op_sel_hi:[0,1]
	v_pk_mul_f32 v[128:129], v[130:131], v[128:129] op_sel_hi:[0,1]
	v_pk_mul_f32 v[132:133], v[40:41], v[126:127]
	v_pk_mul_f32 v[134:135], v[42:43], v[128:129]
	v_pk_mul_f32 v[132:133], v[132:133], v[140:141]
	v_pk_mul_f32 v[134:135], v[134:135], v[142:143]
	v_cvt_pk_bf16_f32 v132, v132, v133
	v_cvt_pk_bf16_f32 v133, v134, v135
	global_store_dwordx2 v[124:125], v[132:133], off offset:256
	v_fmamk_f32 v154, v154, 0x3b800000, v3
	v_mul_f32_e32 v160, 0x4f800000, v154
	v_cmp_gt_f32_e32 vcc, s14, v154
	s_nop 1
	v_cndmask_b32_e32 v154, v154, v160, vcc
	v_sqrt_f32_e32 v160, v154
	s_nop 0
	v_add_u32_e32 v161, -1, v160
	v_add_u32_e32 v162, 1, v160
	v_fma_f32 v163, -v161, v160, v154
	v_fma_f32 v155, -v162, v160, v154
	v_cmp_ge_f32_e64 s[0:1], 0, v163
	s_nop 1
	v_cndmask_b32_e64 v160, v160, v161, s[0:1]
	v_cmp_lt_f32_e64 s[0:1], 0, v155
	s_nop 1
	v_cndmask_b32_e64 v160, v160, v162, s[0:1]
	v_mul_f32_e32 v161, 0x37800000, v160
	v_cndmask_b32_e32 v160, v160, v161, vcc
	v_cmp_class_f32_e32 vcc, v154, v4
	s_nop 1
	v_cndmask_b32_e32 v154, v160, v154, vcc
	v_div_scale_f32 v160, s[0:1], v154, v154, 1.0
	v_rcp_f32_e32 v162, v160
	v_div_scale_f32 v161, vcc, 1.0, v154, 1.0
	v_fma_f32 v163, -v160, v162, 1.0
	v_fmac_f32_e32 v162, v163, v162
	v_mul_f32_e32 v163, v161, v162
	v_fma_f32 v155, -v160, v163, v161
	v_fmac_f32_e32 v163, v155, v162
	v_fma_f32 v160, -v160, v163, v161
	v_div_fmas_f32 v160, v160, v162, v163
	v_div_fixup_f32 v154, v160, v154, 1.0
	v_pk_mul_f32 v[150:151], v[154:155], v[150:151] op_sel_hi:[0,1]
	v_pk_mul_f32 v[152:153], v[154:155], v[152:153] op_sel_hi:[0,1]
	v_pk_mul_f32 v[156:157], v[40:41], v[150:151]
	v_pk_mul_f32 v[158:159], v[42:43], v[152:153]
	v_pk_mul_f32 v[156:157], v[156:157], v[164:165]
	v_pk_mul_f32 v[158:159], v[158:159], v[166:167]
	v_cvt_pk_bf16_f32 v156, v156, v157
	v_cvt_pk_bf16_f32 v157, v158, v159
	global_store_dwordx2 v[148:149], v[156:157], off offset:256
	v_fmamk_f32 v178, v178, 0x3b800000, v3
	v_mul_f32_e32 v184, 0x4f800000, v178
	v_cmp_gt_f32_e32 vcc, s14, v178
	s_nop 1
	v_cndmask_b32_e32 v178, v178, v184, vcc
	v_sqrt_f32_e32 v184, v178
	s_nop 0
	v_add_u32_e32 v185, -1, v184
	v_add_u32_e32 v186, 1, v184
	v_fma_f32 v187, -v185, v184, v178
	v_fma_f32 v179, -v186, v184, v178
; __device__ __forceinline__ float bf_lo(u32 v) { return __uint_as_float(v << 16); }
; __device__ __forceinline__ float bf_hi(u32 v) { return __uint_as_float(v & 0xffff0000u); }
; __device__ __forceinline__ void ret_final_item(const Params& p, int item, const int wv) {
;     ...
;   const float rstd = 1.0f / sqrtf(ss * (1.0f / 256.f) + EPS);
;   const float4 g = *(const float4*)(p.rn_g + h * 256 + lane * 4);
;   const uint2 gv = *(const uint2*)Y;
;   uint2 pk;
;   pk.x = pack2(o0 * rstd * g.x * bf_lo(gv.x), o1 * rstd * g.y * bf_hi(gv.x));
;   pk.y = pack2(o2 * rstd * g.z * bf_lo(gv.y), o3 * rstd * g.w * bf_hi(gv.y));
;   *(uint2*)Y = pk;
; __global__ void __launch_bounds__(512) fwd_megakernel(Params p) {
;     ...
;   for (int it = blockIdx.x; it < 16384; it += gridDim.x) ret_final_item(p, it, wv);
	v_cmp_ge_f32_e64 s[0:1], 0, v187
	s_nop 1
	v_cndmask_b32_e64 v184, v184, v185, s[0:1]
	v_cmp_lt_f32_e64 s[0:1], 0, v179
	s_nop 1
	v_cndmask_b32_e64 v184, v184, v186, s[0:1]
	v_mul_f32_e32 v185, 0x37800000, v184
	v_cndmask_b32_e32 v184, v184, v185, vcc
	v_cmp_class_f32_e32 vcc, v178, v4
	s_nop 1
	v_cndmask_b32_e32 v178, v184, v178, vcc
	v_div_scale_f32 v184, s[0:1], v178, v178, 1.0
	v_rcp_f32_e32 v186, v184
	v_div_scale_f32 v185, vcc, 1.0, v178, 1.0
	v_fma_f32 v187, -v184, v186, 1.0
	v_fmac_f32_e32 v186, v187, v186
	v_mul_f32_e32 v187, v185, v186
	v_fma_f32 v179, -v184, v187, v185
	v_fmac_f32_e32 v187, v179, v186
	v_fma_f32 v184, -v184, v187, v185
	v_div_fmas_f32 v184, v184, v186, v187
	v_div_fixup_f32 v178, v184, v178, 1.0
	v_pk_mul_f32 v[174:175], v[178:179], v[174:175] op_sel_hi:[0,1]
	v_pk_mul_f32 v[176:177], v[178:179], v[176:177] op_sel_hi:[0,1]
	v_pk_mul_f32 v[180:181], v[40:41], v[174:175]
	v_pk_mul_f32 v[182:183], v[42:43], v[176:177]
	v_pk_mul_f32 v[180:181], v[180:181], v[188:189]
	v_pk_mul_f32 v[182:183], v[182:183], v[190:191]
	v_cvt_pk_bf16_f32 v180, v180, v181
	v_cvt_pk_bf16_f32 v181, v182, v183
	global_store_dwordx2 v[172:173], v[180:181], off offset:256
	v_fmamk_f32 v202, v202, 0x3b800000, v3
	v_mul_f32_e32 v208, 0x4f800000, v202
	v_cmp_gt_f32_e32 vcc, s14, v202
	s_nop 1
	v_cndmask_b32_e32 v202, v202, v208, vcc
	v_sqrt_f32_e32 v208, v202
	s_nop 0
	v_add_u32_e32 v209, -1, v208
	v_add_u32_e32 v210, 1, v208
	v_fma_f32 v211, -v209, v208, v202
	v_fma_f32 v203, -v210, v208, v202
	v_cmp_ge_f32_e64 s[0:1], 0, v211
	s_nop 1
	v_cndmask_b32_e64 v208, v208, v209, s[0:1]
	v_cmp_lt_f32_e64 s[0:1], 0, v203
	s_nop 1
	v_cndmask_b32_e64 v208, v208, v210, s[0:1]
	v_mul_f32_e32 v209, 0x37800000, v208
	v_cndmask_b32_e32 v208, v208, v209, vcc
	v_cmp_class_f32_e32 vcc, v202, v4
	s_nop 1
	v_cndmask_b32_e32 v202, v208, v202, vcc
	v_div_scale_f32 v208, s[0:1], v202, v202, 1.0
	v_rcp_f32_e32 v210, v208
	v_div_scale_f32 v209, vcc, 1.0, v202, 1.0
	v_fma_f32 v211, -v208, v210, 1.0
	v_fmac_f32_e32 v210, v211, v210
	v_mul_f32_e32 v211, v209, v210
	v_fma_f32 v203, -v208, v211, v209
	v_fmac_f32_e32 v211, v203, v210
	v_fma_f32 v208, -v208, v211, v209
	v_div_fmas_f32 v208, v208, v210, v211
	v_div_fixup_f32 v202, v208, v202, 1.0
	v_pk_mul_f32 v[198:199], v[202:203], v[198:199] op_sel_hi:[0,1]
	v_pk_mul_f32 v[200:201], v[202:203], v[200:201] op_sel_hi:[0,1]
	v_pk_mul_f32 v[204:205], v[40:41], v[198:199]
	v_pk_mul_f32 v[206:207], v[42:43], v[200:201]
	v_pk_mul_f32 v[204:205], v[204:205], v[212:213]
	v_pk_mul_f32 v[206:207], v[206:207], v[214:215]
	v_cvt_pk_bf16_f32 v204, v204, v205
	v_cvt_pk_bf16_f32 v205, v206, v207
	global_store_dwordx2 v[196:197], v[204:205], off offset:256
	v_fmamk_f32 v226, v226, 0x3b800000, v3
	v_mul_f32_e32 v232, 0x4f800000, v226
	v_cmp_gt_f32_e32 vcc, s14, v226
	s_nop 1
	v_cndmask_b32_e32 v226, v226, v232, vcc
	v_sqrt_f32_e32 v232, v226
	s_nop 0
	v_add_u32_e32 v233, -1, v232
	v_add_u32_e32 v234, 1, v232
	v_fma_f32 v235, -v233, v232, v226
	v_fma_f32 v227, -v234, v232, v226
	v_cmp_ge_f32_e64 s[0:1], 0, v235
	s_nop 1
	v_cndmask_b32_e64 v232, v232, v233, s[0:1]
	v_cmp_lt_f32_e64 s[0:1], 0, v227
	s_nop 1
	v_cndmask_b32_e64 v232, v232, v234, s[0:1]
	v_mul_f32_e32 v233, 0x37800000, v232
	v_cndmask_b32_e32 v232, v232, v233, vcc
	v_cmp_class_f32_e32 vcc, v226, v4
	s_nop 1
	v_cndmask_b32_e32 v226, v232, v226, vcc
	v_div_scale_f32 v232, s[0:1], v226, v226, 1.0
	v_rcp_f32_e32 v234, v232
	v_div_scale_f32 v233, vcc, 1.0, v226, 1.0
	v_fma_f32 v235, -v232, v234, 1.0
	v_fmac_f32_e32 v234, v235, v234
	v_mul_f32_e32 v235, v233, v234
	v_fma_f32 v227, -v232, v235, v233
	v_fmac_f32_e32 v235, v227, v234
	v_fma_f32 v232, -v232, v235, v233
	v_div_fmas_f32 v232, v232, v234, v235
	v_div_fixup_f32 v226, v232, v226, 1.0
	v_pk_mul_f32 v[222:223], v[226:227], v[222:223] op_sel_hi:[0,1]
	v_pk_mul_f32 v[224:225], v[226:227], v[224:225] op_sel_hi:[0,1]
	v_pk_mul_f32 v[228:229], v[40:41], v[222:223]
	v_pk_mul_f32 v[230:231], v[42:43], v[224:225]
	v_pk_mul_f32 v[228:229], v[228:229], v[236:237]
	v_pk_mul_f32 v[230:231], v[230:231], v[238:239]
	v_cvt_pk_bf16_f32 v228, v228, v229
	v_cvt_pk_bf16_f32 v229, v230, v231
	global_store_dwordx2 v[220:221], v[228:229], off offset:256
	s_branch .Lrf_check
.Lrf_tail:
	s_cmpk_gt_i32 s15, 0x3fff
	s_cbranch_scc1 .LBB0_764
